# MoBA K / V^T LDS tiles: rows interleaved inside every 32-row group so the MFMA fragment reads are bank-conflict-free (writers and readers changed consistently)
# speedup vs baseline: 1.0098x; 1.0098x over previous
.LBB0_87:
	s_or_b64 exec, exec, s[4:5]
	v_readlane_b32 s0, v252, 9
	v_readlane_b32 s1, v252, 10
	s_waitcnt vmcnt(2)
	v_mov_b32_e32 v4, v173
	s_andn2_b64 vcc, exec, s[0:1]
	s_barrier
	s_cbranch_vccnz .LBB0_159
	v_ashrrev_i32_e32 v1, 2, v4
	v_readlane_b32 s0, v253, 37
	v_bfi_b32 v157, -16, v1, v4
	s_waitcnt lgkmcnt(0)
	v_and_b32_e32 v5, 15, v4
	v_and_b32_e32 v6, -16, v1
	v_and_b32_e32 v8, 0x7f, v4
	v_mov_b32_e32 v10, s0
	s_movk_i32 s1, 0x84
	s_movk_i32 s0, 0x80
	v_mul_lo_u32 v1, v157, s64
	v_mul_u32_u24_e32 v135, 0x110, v8
	v_mad_u32_u24 v8, v8, s1, v10
	v_cmp_gt_i32_e64 s[4:5], s0, v4
	v_add_u32_e32 v10, 0, v1
	v_lshlrev_b32_e32 v1, 2, v6
	v_lshlrev_b32_e32 v6, 2, v5
	v_readlane_b32 s0, v253, 38
	v_and_b32_e32 v7, 63, v4
	v_lshlrev_b32_e32 v0, 4, v5
	v_add3_u32 v159, s0, v1, v6
	v_and_b32_e32 v6, 64, v214
	v_xor_b32_e32 v1, 1, v214
	v_add_u32_e32 v6, 64, v6
	v_cmp_lt_i32_e32 vcc, v1, v6
	v_lshl_add_u32 v164, v7, 2, s0
	v_and_b32_e32 v7, 3, v4
	v_cndmask_b32_e32 v1, v214, v1, vcc
	v_lshlrev_b32_e32 v160, 2, v1
	v_xor_b32_e32 v1, 2, v214
	v_cmp_lt_i32_e32 vcc, v1, v6
	v_lshlrev_b32_e32 v11, 5, v7
	v_subrev_u32_e32 v12, 56, v11
	v_cndmask_b32_e32 v1, v214, v1, vcc
	v_lshlrev_b32_e32 v161, 2, v1
	v_xor_b32_e32 v1, 4, v214
	v_cmp_lt_i32_e32 vcc, v1, v6
	v_readlane_b32 s6, v254, 48
	v_readlane_b32 s7, v254, 49
	v_cndmask_b32_e32 v1, v214, v1, vcc
	v_lshlrev_b32_e32 v162, 2, v1
	v_xor_b32_e32 v1, 8, v214
	v_cmp_lt_i32_e32 vcc, v1, v6
	v_lshlrev_b32_e32 v2, 3, v5
	v_mul_u32_u24_e32 v167, 0x220, v5
	v_cndmask_b32_e32 v1, v214, v1, vcc
	v_cmp_gt_u32_e32 vcc, 2, v7
	v_lshlrev_b32_e32 v163, 2, v1
	v_and_b32_e32 v1, 0xc0, v0
	v_cndmask_b32_e32 v7, v12, v11, vcc
	v_add_u32_e32 v165, v7, v1
	v_mov_b32_e32 v1, v3
	v_lshl_add_u64 v[118:119], s[6:7], 0, v[0:1]
	v_lshrrev_b32_e32 v1, 2, v4
	v_and_b32_e32 v120, 12, v1
	v_xor_b32_e32 v1, 16, v214
	v_cmp_lt_i32_e32 vcc, v1, v6
	v_add_u32_e32 v5, 0x400, v4
	v_ashrrev_i32_e32 v124, 4, v5
	v_cndmask_b32_e32 v1, v214, v1, vcc
	v_lshlrev_b32_e32 v168, 2, v1
	v_xor_b32_e32 v1, 32, v214
	v_cmp_lt_i32_e32 vcc, v1, v6
	v_add_u32_e32 v5, 0x600, v4
	v_ashrrev_i32_e32 v9, 7, v4
	v_cndmask_b32_e32 v1, v214, v1, vcc
	v_lshl_add_u32 v166, v4, 2, s0
	v_lshlrev_b32_e32 v169, 2, v1
	v_add_u32_e32 v1, 0x200, v4
	v_ashrrev_i32_e32 v126, 4, v5
	v_ashrrev_i32_e32 v5, 31, v4
	v_readlane_b32 s0, v253, 36
	v_and_b32_e32 v158, 48, v4
	v_ashrrev_i32_e32 v116, 4, v4
	v_mul_lo_u32 v7, v4, s1
	v_ashrrev_i32_e32 v122, 4, v1
	v_lshl_add_u32 v171, v4, 4, s0
	v_lshl_add_u32 v175, v1, 4, s0
	v_lshlrev_b32_e32 v1, 3, v9
	v_lshl_add_u64 v[4:5], v[4:5], 4, s[6:7]
	s_mov_b64 s[0:1], 0x13ec0400
	v_add_u32_e32 v133, 0, v0
	v_add_u32_e32 v11, 0, v165
	v_mul_lo_u32 v170, v116, s64
	v_and_b32_e32 v216, 15, v116
	v_lshrrev_b32_e32 v217, 4, v116
	v_lshl_add_u32 v216, v216, 1, v217
	v_mul_u32_u24_e32 v216, 0x110, v216
	v_add_u32_e32 v217, v133, v216
	v_mul_lo_u32 v6, v122, s64
	v_mul_lo_u32 v12, v124, s64
	v_mul_lo_u32 v13, v126, s64
	v_or_b32_e32 v130, 2, v1
	v_or_b32_e32 v132, 4, v1
	v_or_b32_e32 v134, 6, v1
	v_lshl_add_u64 v[136:137], v[4:5], 0, s[0:1]
	v_add_u32_e32 v4, 0, v7
	v_lshlrev_b32_e32 v156, 12, v9
	v_ashrrev_i32_e32 v117, 31, v116
	v_ashrrev_i32_e32 v123, 31, v122
	v_ashrrev_i32_e32 v125, 31, v124
	v_ashrrev_i32_e32 v127, 31, v126
	v_lshl_add_u32 v184, v9, 5, v8
	v_or_b32_e32 v128, 1, v1
	v_or_b32_e32 v121, 3, v1
	v_lshl_add_u32 v185, v130, 2, v8
	v_or_b32_e32 v129, 5, v1
	v_lshl_add_u32 v186, v132, 2, v8
	v_or_b32_e32 v131, 7, v1
	v_lshl_add_u32 v187, v134, 2, v8
	v_lshlrev_b32_e32 v2, 1, v2
	v_add_u32_e32 v188, v133, v6
	v_add_u32_e32 v189, v133, v12
	v_add_u32_e32 v190, v133, v13
	v_add_u32_e32 v191, 0x15000, v4
	v_add_u32_e32 v192, v10, v158
	v_add_u32_e32 v193, v11, v216
	v_lshlrev_b32_e32 v138, 1, v120
	s_mov_b32 s42, s66
	s_branch .LBB0_90

.LBB0_132:
	s_waitcnt lgkmcnt(0)
	s_barrier
	s_and_b64 vcc, exec, s[0:1]
	s_cbranch_vccnz .LBB0_135
	v_add_u32_e32 v53, 0x8800, v193
	s_waitcnt vmcnt(7)
	ds_write_b128 v217, v[4:7]
	s_waitcnt vmcnt(6)
	ds_write2_b64 v53, v[8:9], v[10:11] offset1:2
	s_waitcnt vmcnt(5)
	ds_write_b128 v217, v[12:15] offset:8704
	v_add_u32_e32 v53, 0xa800, v193
	s_waitcnt vmcnt(4)
	ds_write2_b64 v53, v[16:17], v[18:19] offset0:64 offset1:66
	s_waitcnt vmcnt(3)
	ds_write_b128 v217, v[20:23] offset:17408
	v_add_u32_e32 v53, 0xc800, v193
	s_waitcnt vmcnt(2)
	ds_write2_b64 v53, v[24:25], v[26:27] offset0:128 offset1:130
	s_waitcnt vmcnt(1)
	ds_write_b128 v217, v[28:31] offset:26112
	v_add_u32_e32 v52, 0xe800, v193
	s_andn2_b64 vcc, exec, s[10:11]
	s_waitcnt vmcnt(0)
	ds_write2_b64 v52, v[32:33], v[34:35] offset0:192 offset1:194
	s_cbranch_vccnz .LBB0_135
	s_lshr_b32 s0, s14, 1
	s_sub_i32 s0, s47, s0
	s_lshl_b32 s1, s14, 7
	s_lshl_b32 s0, s0, 8
	s_and_b32 s1, s1, 0x80
	s_or_b32 s0, s0, s1
	s_ashr_i32 s1, s0, 31
	v_lshl_add_u64 v[4:5], v[140:141], 0, s[0:1]
	v_mov_b64_e32 v[6:7], s[88:89]
	v_lshl_add_u64 v[28:29], s[0:1], 1, v[118:119]
	v_mad_u64_u32 v[6:7], s[0:1], v4, s72, v[6:7]
	v_mad_i32_i24 v7, v5, s72, v7
	v_lshl_add_u64 v[4:5], v[6:7], 0, s[20:21]
	v_lshl_add_u64 v[30:31], v[4:5], 0, v[2:3]
	v_add_co_u32_e32 v4, vcc, s3, v30
	s_mov_b32 s0, 0x3d000
	s_nop 0
	v_addc_co_u32_e32 v5, vcc, 0, v31, vcc
	v_add_co_u32_e32 v12, vcc, s0, v30
	v_lshl_add_u64 v[8:9], v[28:29], 0, v[146:147]
	s_nop 0
	v_addc_co_u32_e32 v13, vcc, 0, v31, vcc
	v_add_co_u32_e32 v20, vcc, 0x79000, v30
	v_lshl_add_u64 v[16:17], v[28:29], 0, v[148:149]
	s_nop 0
	v_addc_co_u32_e32 v21, vcc, 0, v31, vcc
	v_add_co_u32_e32 v30, vcc, 0xb5000, v30
	v_lshl_add_u64 v[24:25], v[28:29], 0, v[150:151]
	s_nop 0
	v_addc_co_u32_e32 v31, vcc, 0, v31, vcc
	v_lshl_add_u64 v[32:33], v[28:29], 0, v[152:153]
	global_load_dwordx4 v[4:7], v[4:5], off offset:1024
	s_nop 0
	global_load_dwordx4 v[8:11], v[8:9], off
	s_nop 0
	global_load_dwordx4 v[12:15], v[12:13], off offset:1024
	s_nop 0
	global_load_dwordx4 v[16:19], v[16:17], off
	s_nop 0
	global_load_dwordx4 v[20:23], v[20:21], off offset:1024
	s_nop 0
	global_load_dwordx4 v[24:27], v[24:25], off
	s_nop 0
	global_load_dwordx4 v[28:31], v[30:31], off offset:1024
	s_nop 0
	global_load_dwordx4 v[32:35], v[32:33], off

.LBB0_148:
	s_cmp_ge_i32 s16, s48
	s_cselect_b64 s[8:9], -1, 0
	s_and_b64 vcc, exec, s[8:9]
	s_cbranch_vccnz .LBB0_151
	s_xor_b32 s10, s15, 1
	s_mul_i32 s10, s10, 0x11000
	s_add_i32 s10, s10, 0
	v_add3_u32 v85, s10, v165, v216
	v_add3_u32 v84, s10, v0, v216
	v_add_u32_e32 v86, 0x8800, v85
	s_waitcnt vmcnt(7)
	ds_write_b128 v84, v[4:7]
	s_waitcnt vmcnt(6)
	ds_write2_b64 v86, v[8:9], v[10:11] offset1:2
	s_waitcnt vmcnt(5)
	ds_write_b128 v84, v[12:15] offset:8704
	v_add_u32_e32 v86, 0xa800, v85
	s_waitcnt vmcnt(4)
	ds_write2_b64 v86, v[16:17], v[18:19] offset0:64 offset1:66
	s_waitcnt vmcnt(3)
	ds_write_b128 v84, v[20:23] offset:17408
	v_add_u32_e32 v86, 0xc800, v85
	s_waitcnt vmcnt(2)
	ds_write2_b64 v86, v[24:25], v[26:27] offset0:128 offset1:130
	s_waitcnt vmcnt(1)
	ds_write_b128 v84, v[28:31] offset:26112
	v_add_u32_e32 v84, 0xe800, v85
	s_andn2_b64 vcc, exec, s[0:1]
	s_waitcnt vmcnt(0)
	ds_write2_b64 v84, v[32:33], v[34:35] offset0:192 offset1:194
	s_cbranch_vccnz .LBB0_151
	s_lshr_b32 s0, s14, 1
	s_sub_i32 s0, s47, s0
	s_lshl_b32 s1, s14, 7
	s_lshl_b32 s0, s0, 8
	s_and_b32 s1, s1, 0x80
	s_or_b32 s0, s0, s1
	s_ashr_i32 s1, s0, 31
	v_lshl_add_u64 v[4:5], v[140:141], 0, s[0:1]
	v_mov_b64_e32 v[6:7], s[88:89]
	v_lshl_add_u64 v[28:29], s[0:1], 1, v[118:119]
	v_mad_u64_u32 v[6:7], s[0:1], v4, s72, v[6:7]
	v_mad_i32_i24 v7, v5, s72, v7
	v_lshl_add_u64 v[4:5], v[6:7], 0, s[20:21]
	v_lshl_add_u64 v[30:31], v[4:5], 0, v[2:3]
	v_add_co_u32_e32 v4, vcc, s3, v30
	s_mov_b32 s0, 0x3d000
	s_nop 0
	v_addc_co_u32_e32 v5, vcc, 0, v31, vcc
	v_add_co_u32_e32 v12, vcc, s0, v30
	v_lshl_add_u64 v[8:9], v[28:29], 0, v[146:147]
	s_nop 0
	v_addc_co_u32_e32 v13, vcc, 0, v31, vcc
	v_add_co_u32_e32 v20, vcc, 0x79000, v30
	v_lshl_add_u64 v[16:17], v[28:29], 0, v[148:149]
	s_nop 0
	v_addc_co_u32_e32 v21, vcc, 0, v31, vcc
	v_add_co_u32_e32 v30, vcc, 0xb5000, v30
	v_lshl_add_u64 v[24:25], v[28:29], 0, v[150:151]
	s_nop 0
	v_addc_co_u32_e32 v31, vcc, 0, v31, vcc
	v_lshl_add_u64 v[32:33], v[28:29], 0, v[152:153]
	global_load_dwordx4 v[4:7], v[4:5], off offset:1024
	s_nop 0
	global_load_dwordx4 v[8:11], v[8:9], off
	s_nop 0
	global_load_dwordx4 v[12:15], v[12:13], off offset:1024
	s_nop 0
	global_load_dwordx4 v[16:19], v[16:17], off
	s_nop 0
	global_load_dwordx4 v[20:23], v[20:21], off offset:1024
	s_nop 0
	global_load_dwordx4 v[24:27], v[24:25], off
	s_nop 0
	global_load_dwordx4 v[28:31], v[30:31], off offset:1024
	s_nop 0
	global_load_dwordx4 v[32:35], v[32:33], off
.LBB0_151:
	s_ashr_i32 s0, s51, 1
	s_sub_i32 s0, s47, s0
	s_lshl_b32 s0, 1, s0
	s_and_b32 s1, s0, s49
	s_cmp_eq_u32 s1, 0
	s_cbranch_scc1 .LBB0_137
	s_mul_i32 s1, s15, 0x11000
	s_add_i32 s1, s1, 0
	v_add_u32_e32 v84, s1, v167
	v_add_u32_e32 v195, v84, v158
	v_add3_u32 v197, s1, v158, v167
	ds_read_b128 v[84:87], v195
	ds_read_b128 v[88:91], v195 offset:64
	ds_read_b128 v[92:95], v195 offset:128
	ds_read_b128 v[96:99], v195 offset:192
	ds_read_b128 v[100:103], v197 offset:272
	ds_read_b128 v[104:107], v197 offset:336
	ds_read_b128 v[108:111], v197 offset:400
	ds_read_b128 v[198:201], v197 offset:464
	s_waitcnt lgkmcnt(4)
	v_mfma_f32_16x16x32_bf16 v[84:87], v[84:87], v[36:39], 0
	v_mfma_f32_16x16x32_bf16 v[84:87], v[88:91], v[40:43], v[84:87]
	v_mfma_f32_16x16x32_bf16 v[84:87], v[92:95], v[44:47], v[84:87]
	v_mfma_f32_16x16x32_bf16 v[112:115], v[96:99], v[48:51], v[84:87]
	s_nop 5
	ds_read_b128 v[84:87], v197 offset:8704
	ds_read_b128 v[88:91], v197 offset:8768
	ds_read_b128 v[92:95], v197 offset:8832
	ds_read_b128 v[96:99], v197 offset:8896
	s_waitcnt lgkmcnt(4)
	v_mfma_f32_16x16x32_bf16 v[100:103], v[100:103], v[36:39], 0
	v_mfma_f32_16x16x32_bf16 v[100:103], v[104:107], v[40:43], v[100:103]
	v_mfma_f32_16x16x32_bf16 v[100:103], v[108:111], v[44:47], v[100:103]
	v_mfma_f32_16x16x32_bf16 v[108:111], v[198:201], v[48:51], v[100:103]
	s_nop 5
	ds_read_b128 v[100:103], v197 offset:8976
	ds_read_b128 v[198:201], v197 offset:9040
	ds_read_b128 v[202:205], v197 offset:9104
	ds_read_b128 v[206:209], v197 offset:9168
	s_waitcnt lgkmcnt(4)
	v_mfma_f32_16x16x32_bf16 v[84:87], v[84:87], v[36:39], 0
	v_mfma_f32_16x16x32_bf16 v[84:87], v[88:91], v[40:43], v[84:87]
	v_mfma_f32_16x16x32_bf16 v[84:87], v[92:95], v[44:47], v[84:87]
	v_mfma_f32_16x16x32_bf16 v[104:107], v[96:99], v[48:51], v[84:87]
	s_nop 5
	ds_read_b128 v[84:87], v197 offset:17408
	ds_read_b128 v[88:91], v197 offset:17472
	ds_read_b128 v[92:95], v197 offset:17536
	ds_read_b128 v[96:99], v197 offset:17600
	s_waitcnt lgkmcnt(4)
	v_mfma_f32_16x16x32_bf16 v[100:103], v[100:103], v[36:39], 0
	v_mfma_f32_16x16x32_bf16 v[100:103], v[198:201], v[40:43], v[100:103]
	v_mfma_f32_16x16x32_bf16 v[100:103], v[202:205], v[44:47], v[100:103]
	v_mfma_f32_16x16x32_bf16 v[100:103], v[206:209], v[48:51], v[100:103]
	ds_read_b128 v[198:201], v197 offset:17680
	ds_read_b128 v[202:205], v197 offset:17744
	ds_read_b128 v[206:209], v197 offset:17808
	ds_read_b128 v[230:233], v197 offset:17872
	s_waitcnt lgkmcnt(4)
	v_mfma_f32_16x16x32_bf16 v[84:87], v[84:87], v[36:39], 0
	v_mfma_f32_16x16x32_bf16 v[84:87], v[88:91], v[40:43], v[84:87]
	v_mfma_f32_16x16x32_bf16 v[84:87], v[92:95], v[44:47], v[84:87]
	v_mfma_f32_16x16x32_bf16 v[96:99], v[96:99], v[48:51], v[84:87]
	s_nop 5
	ds_read_b128 v[84:87], v197 offset:26112
	ds_read_b128 v[88:91], v197 offset:26176
	ds_read_b128 v[234:237], v197 offset:26240
	ds_read_b128 v[238:241], v197 offset:26304
	s_waitcnt lgkmcnt(4)
	v_mfma_f32_16x16x32_bf16 v[92:95], v[198:201], v[36:39], 0
	v_mfma_f32_16x16x32_bf16 v[92:95], v[202:205], v[40:43], v[92:95]
	v_mfma_f32_16x16x32_bf16 v[92:95], v[206:209], v[44:47], v[92:95]
	v_mfma_f32_16x16x32_bf16 v[92:95], v[230:233], v[48:51], v[92:95]
	ds_read_b128 v[198:201], v197 offset:26384
	ds_read_b128 v[202:205], v197 offset:26448
	ds_read_b128 v[206:209], v197 offset:26512
	ds_read_b128 v[230:233], v197 offset:26576
	s_waitcnt lgkmcnt(4)
	v_mfma_f32_16x16x32_bf16 v[84:87], v[84:87], v[36:39], 0
	v_mfma_f32_16x16x32_bf16 v[84:87], v[88:91], v[40:43], v[84:87]
	v_mfma_f32_16x16x32_bf16 v[84:87], v[234:237], v[44:47], v[84:87]
	v_mfma_f32_16x16x32_bf16 v[88:91], v[238:241], v[48:51], v[84:87]
	s_waitcnt lgkmcnt(0)
	v_mfma_f32_16x16x32_bf16 v[84:87], v[198:201], v[36:39], 0
	v_mfma_f32_16x16x32_bf16 v[84:87], v[202:205], v[40:43], v[84:87]
	v_mfma_f32_16x16x32_bf16 v[84:87], v[206:209], v[44:47], v[84:87]
	v_mfma_f32_16x16x32_bf16 v[84:87], v[230:233], v[48:51], v[84:87]
	ds_read_b128 v[202:205], v195 offset:34816
	ds_read_b128 v[206:209], v195 offset:35088
	ds_read_b128 v[230:233], v195 offset:43520
	ds_read_b128 v[234:237], v195 offset:43792
	v_and_b32_e32 v197, s0, v139
	v_cmp_eq_u32_e64 s[0:1], 0, v197
	s_cmp_lt_u32 s51, 2
	s_mov_b64 s[10:11], -1
	s_cbranch_scc1 .LBB0_154
	v_max3_f32 v197, v112, v113, v114
	v_max3_f32 v198, v96, v97, v98
	v_max3_f32 v197, v197, v115, v108
	v_max3_f32 v198, v198, v99, v92
	v_max3_f32 v197, v197, v109, v110
	v_max3_f32 v198, v198, v93, v94
	v_max3_f32 v197, v197, v111, v104
	v_max3_f32 v198, v198, v95, v88
	v_max3_f32 v197, v197, v105, v106
	v_max3_f32 v198, v198, v89, v90
	v_max3_f32 v197, v197, v107, v100
	v_max3_f32 v198, v198, v91, v84
	v_max3_f32 v197, v197, v101, v102
	v_max3_f32 v198, v198, v85, v86
	v_max_f32_e32 v197, v197, v103
	v_max_f32_e32 v198, v198, v87
	v_max_f32_e32 v197, v197, v198
	v_cndmask_b32_e64 v197, v197, v215, s[0:1]
	s_mov_b64 s[10:11], 0

.LBB0_158:
	s_waitcnt lgkmcnt(0)
	v_add_f32_e32 v198, v198, v199
	v_fmac_f32_e32 v198, v194, v84
	v_cvt_pk_bf16_f32 v112, v112, v113
	v_cvt_pk_bf16_f32 v113, v114, v115
	v_cvt_pk_bf16_f32 v114, v108, v109
	v_cvt_pk_bf16_f32 v115, v110, v111
	v_cvt_pk_bf16_f32 v104, v104, v105
	v_cvt_pk_bf16_f32 v105, v106, v107
	v_cvt_pk_bf16_f32 v106, v100, v101
	v_cvt_pk_bf16_f32 v107, v102, v103
	v_cvt_pk_bf16_f32 v96, v96, v97
	v_cvt_pk_bf16_f32 v97, v98, v99
	v_cvt_pk_bf16_f32 v98, v92, v93
	v_cvt_pk_bf16_f32 v99, v94, v95
	v_cvt_pk_bf16_f32 v88, v88, v89
	v_cvt_pk_bf16_f32 v89, v90, v91
	v_cvt_pk_bf16_f32 v90, v196, v85
	v_cvt_pk_bf16_f32 v91, v86, v87
	ds_read_b128 v[84:87], v195 offset:52224
	ds_read_b128 v[92:95], v195 offset:52496
	ds_read_b128 v[100:103], v195 offset:60928
	ds_read_b128 v[108:111], v195 offset:61200
	s_waitcnt lgkmcnt(4)
	v_mfma_f32_16x16x32_bf16 v[80:83], v[202:205], v[112:115], v[80:83]
	v_mfma_f32_16x16x32_bf16 v[76:79], v[206:209], v[112:115], v[76:79]
	v_mfma_f32_16x16x32_bf16 v[72:75], v[230:233], v[112:115], v[72:75]
	v_mfma_f32_16x16x32_bf16 v[68:71], v[234:237], v[112:115], v[68:71]
	ds_read_b128 v[202:205], v195 offset:34880
	ds_read_b128 v[206:209], v195 offset:35152
	ds_read_b128 v[230:233], v195 offset:43584
	ds_read_b128 v[234:237], v195 offset:43856
	s_waitcnt lgkmcnt(4)
	v_mfma_f32_16x16x32_bf16 v[64:67], v[84:87], v[112:115], v[64:67]
	v_mfma_f32_16x16x32_bf16 v[60:63], v[92:95], v[112:115], v[60:63]
	v_mfma_f32_16x16x32_bf16 v[56:59], v[100:103], v[112:115], v[56:59]
	v_mfma_f32_16x16x32_bf16 v[52:55], v[108:111], v[112:115], v[52:55]
	ds_read_b128 v[84:87], v195 offset:52288
	ds_read_b128 v[92:95], v195 offset:52560
	ds_read_b128 v[100:103], v195 offset:60992
	ds_read_b128 v[108:111], v195 offset:61264
	s_waitcnt lgkmcnt(4)
	v_mfma_f32_16x16x32_bf16 v[80:83], v[202:205], v[104:107], v[80:83]
	v_mfma_f32_16x16x32_bf16 v[76:79], v[206:209], v[104:107], v[76:79]
	v_mfma_f32_16x16x32_bf16 v[72:75], v[230:233], v[104:107], v[72:75]
	v_mfma_f32_16x16x32_bf16 v[68:71], v[234:237], v[104:107], v[68:71]
	ds_read_b128 v[202:205], v195 offset:34944
	ds_read_b128 v[206:209], v195 offset:35216
	ds_read_b128 v[230:233], v195 offset:43648
	ds_read_b128 v[234:237], v195 offset:43920
	s_waitcnt lgkmcnt(4)
	v_mfma_f32_16x16x32_bf16 v[64:67], v[84:87], v[104:107], v[64:67]
	v_mfma_f32_16x16x32_bf16 v[60:63], v[92:95], v[104:107], v[60:63]
	v_mfma_f32_16x16x32_bf16 v[56:59], v[100:103], v[104:107], v[56:59]
	v_mfma_f32_16x16x32_bf16 v[52:55], v[108:111], v[104:107], v[52:55]
	ds_read_b128 v[84:87], v195 offset:52352
	ds_read_b128 v[92:95], v195 offset:52624
	ds_read_b128 v[100:103], v195 offset:61056
	ds_read_b128 v[108:111], v195 offset:61328
	s_waitcnt lgkmcnt(4)
	v_mfma_f32_16x16x32_bf16 v[80:83], v[202:205], v[96:99], v[80:83]
	v_mfma_f32_16x16x32_bf16 v[76:79], v[206:209], v[96:99], v[76:79]
	v_mfma_f32_16x16x32_bf16 v[72:75], v[230:233], v[96:99], v[72:75]
	v_mfma_f32_16x16x32_bf16 v[68:71], v[234:237], v[96:99], v[68:71]
	ds_read_b128 v[202:205], v195 offset:35008
	ds_read_b128 v[206:209], v195 offset:35280
	ds_read_b128 v[230:233], v195 offset:43712
	ds_read_b128 v[234:237], v195 offset:43984
	s_waitcnt lgkmcnt(4)
	v_mfma_f32_16x16x32_bf16 v[64:67], v[84:87], v[96:99], v[64:67]
	v_mfma_f32_16x16x32_bf16 v[60:63], v[92:95], v[96:99], v[60:63]
	v_mfma_f32_16x16x32_bf16 v[56:59], v[100:103], v[96:99], v[56:59]
	v_mfma_f32_16x16x32_bf16 v[52:55], v[108:111], v[96:99], v[52:55]
	ds_read_b128 v[84:87], v195 offset:52416
	ds_read_b128 v[92:95], v195 offset:52688
	ds_read_b128 v[100:103], v195 offset:61120
	ds_read_b128 v[108:111], v195 offset:61392
	s_waitcnt lgkmcnt(4)
	v_mfma_f32_16x16x32_bf16 v[80:83], v[202:205], v[88:91], v[80:83]
	v_mfma_f32_16x16x32_bf16 v[76:79], v[206:209], v[88:91], v[76:79]
	v_mfma_f32_16x16x32_bf16 v[72:75], v[230:233], v[88:91], v[72:75]
	v_mfma_f32_16x16x32_bf16 v[68:71], v[234:237], v[88:91], v[68:71]
	s_waitcnt lgkmcnt(0)
	v_mfma_f32_16x16x32_bf16 v[64:67], v[84:87], v[88:91], v[64:67]
	v_mfma_f32_16x16x32_bf16 v[60:63], v[92:95], v[88:91], v[60:63]
	v_mfma_f32_16x16x32_bf16 v[56:59], v[100:103], v[88:91], v[56:59]
	v_mfma_f32_16x16x32_bf16 v[52:55], v[108:111], v[88:91], v[52:55]
	v_mov_b32_e32 v194, v198
	s_andn2_b64 vcc, exec, s[8:9]
	s_xor_b32 s15, s15, 1
	s_cbranch_vccnz .LBB0_138
	s_branch .LBB0_92
